# attention loop v2: all 8 waves run one stream, PV MFMAs of the previous half tile interleaved with exp/sum/pack VALU of the current half tile
# speedup vs baseline: 1.0175x; 1.0175x over previous
; #define LAS __attribute__((address_space(3)))
; DI int TID() { int t = threadIdx.x; asm volatile("" : "+v"(t)); return t; }
; template <bool SHIFT> DI void attn_unit(LAS unsigned char* lds, const bf16_t* Qb, const bf16_t* Kb, const bf16_t* Vt, bf16_t* concat,
;                   int b, int h, int qt, float shift2, float lam, int lam_init_bits, const float* subln_g) {
;     const int tid = TID(), wid = __builtin_amdgcn_readfirstlane(tid >> 6), lane = tid & 63, r = lane & 31, hh = lane >> 5;
;     const size_t rowbase = (size_t)b * TPB;
;     const int q0 = qt * 256;
;     const int nkt = (qt == 0) ? 4 : NCH;
;     const bf16_t* kg = Kb + rowbase * 1024 + h * 128;
;     const bf16_t* vg = Vt + ((size_t)(b * 8 + h) * 128) * TPB;
;     const int krow0 = tid >> 4, kc = tid & 15;
;     const int vrow0 = tid >> 3, vc = tid & 7;
; #pragma unroll
;     for (int i = 0; i < 8; ++i) { const int id = i * 512 + tid, row = id >> 4, c = id & 15;
;         const u32x4 v = *(const u32x4*)(Qb + (rowbase + q0 + row) * 1024 + h * 128 + c * 8);
;         *(LAS u32x4*)(lds + Q_OFF + row * QP + c * 16) = v; }
;     u32x4 sg0, sg1;
;     sg0 = *(const u32x4*)(kg + (size_t)(krow0) * 1024 + kc * 8); sg1 = *(const u32x4*)(kg + (size_t)(krow0 + 32) * 1024 + kc * 8);
;     *(LAS u32x4*)(lds + K_OFF + krow0 * QP + kc * 16) = sg0; *(LAS u32x4*)(lds + K_OFF + (krow0 + 32) * QP + kc * 16) = sg1;
;     sg0 = *(const u32x4*)(vg + (size_t)(vrow0) * TPB + vc * 8); sg1 = *(const u32x4*)(vg + (size_t)(vrow0 + 64) * TPB + vc * 8);
;     *(LAS u32x4*)(lds + V_OFF + vrow0 * VP + vc * 16) = sg0; *(LAS u32x4*)(lds + V_OFF + (vrow0 + 64) * VP + vc * 16) = sg1;
;     if (nkt > 1) { sg0 = *(const u32x4*)(kg + (size_t)(64 + krow0) * 1024 + kc * 8); sg1 = *(const u32x4*)(kg + (size_t)(64 + krow0 + 32) * 1024 + kc * 8); }
;     __syncthreads();
;     f32x16 OT[2][4];
; #pragma unroll
;     for (int m = 0; m < 2; ++m)
; #pragma unroll
;         for (int t = 0; t < 4; ++t)
; #pragma unroll
;             for (int i = 0; i < 16; ++i) OT[m][t][i] = 0.f;
;     float lsum[2] = {0.f, 0.f};
;     ...
;     const bool lag = wid >= 4;
;     bf16x8 Pc[2][2];
; #pragma unroll
;     for (int m = 0; m < 2; ++m)
; #pragma unroll
;         for (int g = 0; g < 2; ++g) { u32x4 z = {0u, 0u, 0u, 0u}; Pc[m][g] = __builtin_bit_cast(bf16x8, z); }
.LBB0_532:
	s_mov_b64 s[4:5], s[0:1]
	s_load_dwordx2 s[20:21], s[4:5], 0xa8
	s_mov_b64 s[4:5], s[0:1]
	s_waitcnt lgkmcnt(0)
	s_load_dwordx2 s[4:5], s[4:5], 0xa8
	s_and_b32 s30, s6, 7
	s_mov_b64 s[6:7], s[0:1]
	s_waitcnt lgkmcnt(0)
	s_load_dwordx2 s[6:7], s[6:7], 0xa8
	s_mov_b64 s[12:13], s[0:1]
	s_waitcnt lgkmcnt(0)
	s_mov_b64 s[14:15], s[0:1]
	s_load_dwordx2 s[12:13], s[12:13], 0xa8
	v_mov_b32_e32 v16, v222
	s_lshl_b32 s18, s22, 3
	s_waitcnt lgkmcnt(0)
	s_load_dwordx2 s[16:17], s[14:15], 0x60
	s_or_b32 s34, s18, s30
	v_readfirstlane_b32 s14, v16
	s_lshl_b32 s37, s23, 8
	s_lshl_b32 s29, s30, 7
	s_ashr_i32 s31, s14, 6
	s_mul_i32 s15, s34, 0x210000
	s_mul_hi_i32 s14, s34, 0x210000
	s_add_u32 s15, s6, s15
	s_addc_u32 s14, s7, s14
	s_add_u32 s18, s15, 0x10788000
	s_mul_i32 s36, s22, 0x2100
	s_addc_u32 s19, s14, 0
	s_mul_hi_i32 s35, s22, 0x2100
	s_add_u32 s14, s36, s37
	s_addc_u32 s15, s35, 0
	s_lshl_b32 s37, s30, 8
	s_add_u32 s20, s20, s37
	v_and_b32_e32 v17, 15, v16
	s_addc_u32 s21, s21, 0
	v_lshlrev_b32_e32 v160, 4, v17
	v_mov_b32_e32 v161, v177
	v_ashrrev_i32_e32 v6, 4, v16
	v_lshl_add_u64 v[0:1], s[20:21], 0, v[160:161]
	s_mov_b64 s[20:21], 0xa488000
	v_ashrrev_i32_e32 v7, 31, v6
	v_lshl_add_u64 v[4:5], v[0:1], 0, s[20:21]
	v_lshl_add_u64 v[0:1], s[14:15], 0, v[6:7]
	v_lshlrev_b64 v[0:1], 11, v[0:1]
	v_lshl_add_u64 v[0:1], v[4:5], 0, v[0:1]
	global_load_dwordx4 v[32:35], v[0:1], off
	s_mov_b64 s[20:21], 0x10000
	v_lshl_add_u64 v[64:65], v[0:1], 0, s[20:21]
	global_load_dwordx4 v[36:39], v[64:65], off
	v_lshl_add_u64 v[64:65], v[64:65], 0, s[20:21]
	global_load_dwordx4 v[40:43], v[64:65], off
	v_lshl_add_u64 v[64:65], v[64:65], 0, s[20:21]
	global_load_dwordx4 v[44:47], v[64:65], off
	v_lshl_add_u64 v[64:65], v[64:65], 0, s[20:21]
	global_load_dwordx4 v[48:51], v[64:65], off
	v_lshl_add_u64 v[64:65], v[64:65], 0, s[20:21]
	global_load_dwordx4 v[52:55], v[64:65], off
	v_lshl_add_u64 v[64:65], v[64:65], 0, s[20:21]
	global_load_dwordx4 v[56:59], v[64:65], off
	v_lshl_add_u64 v[64:65], v[64:65], 0, s[20:21]
	global_load_dwordx4 v[60:63], v[64:65], off
	v_add_u32_e32 v8, 0x200, v16
	v_ashrrev_i32_e32 v8, 4, v8
	v_ashrrev_i32_e32 v9, 31, v8
	v_mul_lo_u32 v210, v6, s54
	v_add_u32_e32 v10, 0, v160
	v_lshl_add_u64 v[12:13], s[14:15], 0, v[8:9]
	v_add_u32_e32 v11, v10, v210
	v_mov_b32_e32 v82, v11
	v_lshlrev_b64 v[12:13], 11, v[12:13]
	v_lshl_add_u64 v[12:13], v[4:5], 0, v[12:13]
	v_add_u32_e32 v9, 0x400, v16
	s_mul_i32 s35, s22, 0x1080000
	s_mul_hi_i32 s30, s22, 0x1080000
	v_ashrrev_i32_e32 v18, 3, v16
	v_add_u32_e32 v19, 64, v18
	v_add3_u32 v20, s47, v210, v160
	v_add_u32_e32 v214, 0x2200, v210
	v_add3_u32 v21, s47, v214, v160
	v_mul_lo_u32 v215, v18, s44
	v_add_u32_e32 v216, 0x2400, v215
	v_bfe_u32 v236, v16, 5, 1
	v_lshlrev_b32_e32 v163, 4, v236
	v_lshlrev_b32_e32 v162, 3, v17
	v_mov_b32_e32 v164, 0
	v_mov_b32_e32 v128, 0
	v_mov_b32_e32 v129, 0
	v_mov_b32_e32 v130, 0
	v_mov_b32_e32 v131, 0
	v_mov_b32_e32 v132, 0
	v_mov_b32_e32 v133, 0
	v_mov_b32_e32 v134, 0
	v_mov_b32_e32 v135, 0
	v_mov_b32_e32 v152, 0
	v_mov_b32_e32 v153, 0
	v_mov_b32_e32 v154, 0
	v_mov_b32_e32 v155, 0
	v_mov_b32_e32 v156, 0
	v_mov_b32_e32 v157, 0
	v_mov_b32_e32 v158, 0
	v_mov_b32_e32 v159, 0
	v_mov_b32_e32 v165, v164
	v_ashrrev_i32_e32 v12, 4, v9
	v_ashrrev_i32_e32 v13, 31, v12
	v_lshl_add_u64 v[14:15], s[14:15], 0, v[12:13]
	v_mad_u64_u32 v[8:9], s[20:21], v8, s54, v[10:11]
	v_lshlrev_b64 v[14:15], 11, v[14:15]
	v_lshl_add_u64 v[14:15], v[4:5], 0, v[14:15]
	v_mad_u64_u32 v[12:13], s[20:21], v12, s54, v[10:11]
	v_add_u32_e32 v8, 0x600, v16
	v_ashrrev_i32_e32 v8, 4, v8
	v_ashrrev_i32_e32 v9, 31, v8
	v_lshl_add_u64 v[14:15], s[14:15], 0, v[8:9]
	v_lshlrev_b64 v[14:15], 11, v[14:15]
	v_lshl_add_u64 v[14:15], v[4:5], 0, v[14:15]
	v_add_u32_e32 v9, 0x800, v16
	v_ashrrev_i32_e32 v12, 4, v9
	v_ashrrev_i32_e32 v13, 31, v12
	v_lshl_add_u64 v[14:15], s[14:15], 0, v[12:13]
	v_mad_u64_u32 v[8:9], s[20:21], v8, s54, v[10:11]
	v_lshlrev_b64 v[14:15], 11, v[14:15]
	v_lshl_add_u64 v[14:15], v[4:5], 0, v[14:15]
	v_mad_u64_u32 v[12:13], s[20:21], v12, s54, v[10:11]
	v_add_u32_e32 v8, 0xa00, v16
	v_ashrrev_i32_e32 v8, 4, v8
	v_ashrrev_i32_e32 v9, 31, v8
	v_lshl_add_u64 v[14:15], s[14:15], 0, v[8:9]
	v_lshlrev_b64 v[14:15], 11, v[14:15]
	v_lshl_add_u64 v[14:15], v[4:5], 0, v[14:15]
	v_add_u32_e32 v9, 0xc00, v16
	v_ashrrev_i32_e32 v12, 4, v9
	v_ashrrev_i32_e32 v13, 31, v12
	v_lshl_add_u64 v[14:15], s[14:15], 0, v[12:13]
	v_mad_u64_u32 v[8:9], s[20:21], v8, s54, v[10:11]
	v_lshlrev_b64 v[14:15], 11, v[14:15]
	v_lshl_add_u64 v[14:15], v[4:5], 0, v[14:15]
	v_mad_u64_u32 v[12:13], s[20:21], v12, s54, v[10:11]
	v_add_u32_e32 v8, 0xe00, v16
	v_ashrrev_i32_e32 v8, 4, v8
	v_ashrrev_i32_e32 v9, 31, v8
	v_lshl_add_u64 v[14:15], s[14:15], 0, v[8:9]
	v_lshlrev_b64 v[14:15], 11, v[14:15]
	v_lshl_add_u64 v[4:5], v[4:5], 0, v[14:15]
	v_mad_u64_u32 v[4:5], s[20:21], v8, s54, v[10:11]
	s_add_u32 s20, s4, s35
	s_addc_u32 s21, s5, s30
	s_add_u32 s20, s20, s37
	v_lshlrev_b64 v[12:13], 11, v[6:7]
	s_addc_u32 s21, s21, 0
	v_lshl_add_u64 v[6:7], s[20:21], 0, v[12:13]
	v_lshl_add_u64 v[8:9], v[6:7], 0, v[160:161]
	s_mov_b32 s20, 0xc588000
	v_add_co_u32_e32 v6, vcc, s20, v8
	s_mov_b32 s20, 0xc598000
	s_nop 0
	v_addc_co_u32_e32 v7, vcc, 0, v9, vcc
	v_add_co_u32_e32 v10, vcc, s20, v8
	s_lshl_b32 s30, s31, 5
	s_nop 0
	v_addc_co_u32_e32 v11, vcc, 0, v9, vcc
	s_cmp_gt_i32 s31, 3
	v_and_b32_e32 v161, 63, v16
	global_load_dwordx4 v[66:69], v[6:7], off
	global_load_dwordx4 v[70:73], v[10:11], off
	v_lshlrev_b32_e32 v10, 4, v16
	v_and_b32_e32 v176, 0x70, v10
	v_mov_b64_e32 v[10:11], s[18:19]
	v_mad_i64_i32 v[14:15], s[18:19], v18, s50, v[10:11]
	v_mad_i64_i32 v[10:11], s[18:19], v19, s50, v[10:11]
	v_lshl_add_u64 v[14:15], v[14:15], 0, v[176:177]
	v_lshl_add_u64 v[10:11], v[10:11], 0, v[176:177]
	s_mov_b32 s18, 0xc5a8000
	v_add3_u32 v19, s43, v216, v176
	global_load_dwordx4 v[74:77], v[14:15], off
	global_load_dwordx4 v[78:81], v[10:11], off
	v_add_co_u32_e32 v10, vcc, s18, v8
	v_add3_u32 v15, s43, v215, v176
	s_nop 0
	v_addc_co_u32_e32 v11, vcc, 0, v9, vcc
	s_mov_b32 s18, 0xc5b8000
	v_add_co_u32_e32 v8, vcc, s18, v8
	v_and_b32_e32 v14, 31, v16
	s_nop 0
	v_addc_co_u32_e32 v9, vcc, 0, v9, vcc
	s_mov_b64 s[18:19], -1
	s_cmp_lt_i32 s31, 4
	s_mov_b64 s[20:21], 0
	s_cmp_eq_u32 s23, 0
	s_cselect_b32 s35, 2, 0x82
	s_lshl_b32 s23, s35, 17
	s_or_b32 s36, s23, 0x20000
	v_mul_u32_u24_e32 v237, 0x110, v14
	v_add3_u32 v212, s47, v237, v163
	global_load_dwordx4 v[144:147], v[10:11], off
	global_load_dwordx4 v[148:151], v[8:9], off
	s_waitcnt vmcnt(2)
; #define LAS __attribute__((address_space(3)))
; #define SB0() __builtin_amdgcn_sched_barrier(0)
; template <bool SHIFT> DI void attn_unit(LAS unsigned char* lds, const bf16_t* Qb, const bf16_t* Kb, const bf16_t* Vt, bf16_t* concat,
;                   int b, int h, int qt, float shift2, float lam, int lam_init_bits, const float* subln_g) {
;     ...
;     f32x16 OT[2][4];
; #pragma unroll
;     for (int m = 0; m < 2; ++m)
; #pragma unroll
;         for (int t = 0; t < 4; ++t)
; #pragma unroll
;             for (int i = 0; i < 16; ++i) OT[m][t][i] = 0.f;
;     float lsum[2] = {0.f, 0.f};
;     const LAS unsigned char* qrow = lds + Q_OFF + (32 * wid + r) * QP + hh * 16;
;     ...
;     const bool lag = wid >= 4;
;     bf16x8 Pc[2][2];
; #pragma unroll
;     for (int m = 0; m < 2; ++m)
; #pragma unroll
;         for (int g = 0; g < 2; ++g) { u32x4 z = {0u, 0u, 0u, 0u}; Pc[m][g] = __builtin_bit_cast(bf16x8, z); }
;     const LAS unsigned char* vold = lds + V_OFF + r * VP + hh * 16;
;     int vcur = 0;
;     for (int kt = 0; kt < nkt; ++kt) {
;         const int cur = kt & 1, nx = cur ^ 1;
;         const int vnx = vcur == 2 ? 0 : vcur + 1;
;         const bool pf = (kt + 1 < nkt);
;         const size_t ko = (size_t)(kt + 1) * 64;
;         if (pf) { *(LAS u32x4*)(lds + K_OFF + nx * K_BYTES + krow0 * QP + kc * 16) = sg0; *(LAS u32x4*)(lds + K_OFF + nx * K_BYTES + (krow0 + 32) * QP + kc * 16) = sg1;
;             sg0 = *(const u32x4*)(vg + (size_t)(vrow0) * TPB + ko + vc * 8); sg1 = *(const u32x4*)(vg + (size_t)(vrow0 + 64) * TPB + ko + vc * 8); }
;         const LAS unsigned char* kb = lds + K_OFF + cur * K_BYTES + r * QP + hh * 16;
;         const LAS unsigned char* vb = lds + V_OFF + vcur * V_BYTES + r * VP + hh * 16;
; #pragma unroll
;         for (int half = 0; half < 2; ++half) {
;             if (lag) PVH(Pc, vold);
;             QKEXP(Pc, half);
;             if (half == 0 && pf) { *(LAS u32x4*)(lds + V_OFF + vnx * V_BYTES + vrow0 * VP + vc * 16) = sg0; *(LAS u32x4*)(lds + V_OFF + vnx * V_BYTES + (vrow0 + 64) * VP + vc * 16) = sg1;
;                 if (kt + 2 < nkt) { sg0 = *(const u32x4*)(kg + (ko + 64 + krow0) * 1024 + kc * 8); sg1 = *(const u32x4*)(kg + (ko + 64 + krow0 + 32) * 1024 + kc * 8); } }
;             vold = vb + half * 64;
;             SB0();
;             if (!lag) PVH(Pc, vold);
	ds_write_b128 v82, v[32:35]
	ds_write_b128 v82, v[36:39] offset:8704
	ds_write_b128 v82, v[40:43] offset:17408
	ds_write_b128 v82, v[44:47] offset:26112
	ds_write_b128 v82, v[48:51] offset:34816
	ds_write_b128 v82, v[52:55] offset:43520
	ds_write_b128 v82, v[56:59] offset:52224
	ds_write_b128 v82, v[60:63] offset:60928
	ds_write_b128 v20, v[66:69]
	ds_write_b128 v21, v[70:73]
	ds_write_b128 v15, v[74:77]
	ds_write_b128 v19, v[78:81]
	v_or_b32_e32 v2, s30, v14
	v_mul_lo_u32 v2, v2, s54
	v_add_u32_e32 v16, 0, v2
	v_mul_u32_u24_e32 v2, 0x90, v14
	v_add3_u32 v213, s43, v2, v163
	v_mov_b32_e32 v2, 0x1080000
	v_mad_i64_i32 v[2:3], s[22:23], s22, v2, v[12:13]
	v_or3_b32 v2, v2, s37, v160
	v_mad_i64_i32 v[0:1], s[72:73], v18, s50, 0
	v_lshl_add_u64 v[166:167], s[4:5], 0, v[2:3]
	v_mov_b32_e32 v2, 0x210000
	v_mad_i64_i32 v[0:1], s[4:5], s34, v2, v[0:1]
	v_or_b32_e32 v0, v0, v176
	v_lshl_add_u64 v[0:1], s[6:7], 0, v[0:1]
	s_mov_b64 s[4:5], 0x10890080
	v_mov_b32_e32 v14, v177
	v_mov_b32_e32 v15, v177
	v_lshl_add_u64 v[168:169], v[0:1], 0, s[4:5]
	v_mov_b32_e32 v0, v177
	v_mov_b32_e32 v1, v177
	v_mov_b32_e32 v2, v177
	v_mov_b32_e32 v3, v177
	v_mov_b32_e32 v4, v177
	v_mov_b32_e32 v5, v177
	v_mov_b32_e32 v6, v177
	v_mov_b32_e32 v7, v177
	v_mov_b32_e32 v8, v177
	v_mov_b32_e32 v9, v177
	v_mov_b32_e32 v10, v177
	v_mov_b32_e32 v11, v177
	v_mov_b32_e32 v12, v177
	v_mov_b32_e32 v13, v177
	v_add_u32_e32 v211, v16, v163
	v_mov_b64_e32 v[62:63], v[14:15]
	v_mov_b64_e32 v[78:79], v[14:15]
	v_mov_b64_e32 v[110:111], v[14:15]
	v_mov_b64_e32 v[30:31], v[14:15]
	v_mov_b64_e32 v[46:47], v[14:15]
	v_mov_b64_e32 v[94:95], v[14:15]
	v_mov_b64_e32 v[126:127], v[14:15]
	s_mov_b64 s[22:23], 0
	v_mov_b64_e32 v[60:61], v[12:13]
	v_mov_b64_e32 v[58:59], v[10:11]
	v_mov_b64_e32 v[56:57], v[8:9]
	v_mov_b64_e32 v[54:55], v[6:7]
	v_mov_b64_e32 v[52:53], v[4:5]
	v_mov_b64_e32 v[50:51], v[2:3]
	v_mov_b64_e32 v[48:49], v[0:1]
	v_mov_b64_e32 v[76:77], v[12:13]
	v_mov_b64_e32 v[74:75], v[10:11]
	v_mov_b64_e32 v[72:73], v[8:9]
	v_mov_b64_e32 v[70:71], v[6:7]
	v_mov_b64_e32 v[68:69], v[4:5]
	v_mov_b64_e32 v[66:67], v[2:3]
	v_mov_b64_e32 v[64:65], v[0:1]
	v_mov_b64_e32 v[108:109], v[12:13]
	v_mov_b64_e32 v[106:107], v[10:11]
	v_mov_b64_e32 v[104:105], v[8:9]
	v_mov_b64_e32 v[102:103], v[6:7]
	v_mov_b64_e32 v[100:101], v[4:5]
	v_mov_b64_e32 v[98:99], v[2:3]
	v_mov_b64_e32 v[96:97], v[0:1]
	v_mov_b64_e32 v[28:29], v[12:13]
	v_mov_b64_e32 v[26:27], v[10:11]
	v_mov_b64_e32 v[24:25], v[8:9]
	v_mov_b64_e32 v[22:23], v[6:7]
	v_mov_b64_e32 v[20:21], v[4:5]
	v_mov_b64_e32 v[18:19], v[2:3]
	v_mov_b64_e32 v[16:17], v[0:1]
	v_mov_b64_e32 v[44:45], v[12:13]
	v_mov_b64_e32 v[42:43], v[10:11]
	v_mov_b64_e32 v[40:41], v[8:9]
	v_mov_b64_e32 v[38:39], v[6:7]
	v_mov_b64_e32 v[36:37], v[4:5]
	v_mov_b64_e32 v[34:35], v[2:3]
	v_mov_b64_e32 v[32:33], v[0:1]
	v_mov_b64_e32 v[92:93], v[12:13]
	v_mov_b64_e32 v[90:91], v[10:11]
	v_mov_b64_e32 v[88:89], v[8:9]
	v_mov_b64_e32 v[86:87], v[6:7]
	v_mov_b64_e32 v[84:85], v[4:5]
	v_mov_b64_e32 v[82:83], v[2:3]
	v_mov_b64_e32 v[80:81], v[0:1]
	v_mov_b64_e32 v[124:125], v[12:13]
	v_mov_b64_e32 v[122:123], v[10:11]
	v_mov_b64_e32 v[120:121], v[8:9]
	v_mov_b64_e32 v[118:119], v[6:7]
	v_mov_b64_e32 v[116:117], v[4:5]
	v_mov_b64_e32 v[114:115], v[2:3]
	v_mov_b64_e32 v[112:113], v[0:1]
	v_mov_b32_e32 v136, v213
	s_mov_b32 s34, 0
	s_waitcnt lgkmcnt(0)
	s_barrier
.LBB0_533:
	s_and_b32 s6, s34, 1
	s_xor_b32 s4, s6, 1
	s_mulk_i32 s4, 0x4400
	s_add_i32 s4, s4, 0x11000
	v_add3_u32 v137, s4, v210, v160
	v_add3_u32 v142, s4, v214, v160
	s_mulk_i32 s6, 0x4400
	v_add_u32_e32 v254, s6, v212
	s_mul_i32 s6, s40, 0x4800
	v_add_u32_e32 v217, s6, v213
	ds_read_b128 v[178:181], v254
	ds_read_b128 v[186:189], v211
	ds_read_b128 v[182:185], v254 offset:32
	ds_read_b128 v[190:193], v211 offset:32
	ds_read_b128 v[228:231], v136
	ds_read_b128 v[232:235], v136 offset:4608
	s_add_i32 s7, s40, 1
	s_cmp_lg_u32 s40, 2
	s_cselect_b32 s65, s7, 0
	s_mul_i32 s37, s65, 0x4800
	s_add_i32 s6, s37, 0x19800
	v_add3_u32 v218, s6, v215, v176
	v_add3_u32 v219, s6, v216, v176
	v_add_co_u32_e32 v138, vcc, 0xffef8000, v168
	s_andn2_b64 s[4:5], exec, s[18:19]
	s_andn2_b64 s[6:7], exec, s[20:21]
	v_addc_co_u32_e32 v139, vcc, -1, v169, vcc
	s_waitcnt vmcnt(0)
	ds_write_b128 v137, v[144:147]
	ds_write_b128 v142, v[148:151]
	global_load_dwordx4 v[144:147], v[138:139], off
	global_load_dwordx4 v[148:151], v[168:169], off
	s_waitcnt lgkmcnt(6)
	v_mfma_f32_32x32x16_bf16 v[238:253], v[178:181], v[186:189], 0
	ds_read_b128 v[178:181], v254 offset:64
	ds_read_b128 v[186:189], v211 offset:64
	s_waitcnt lgkmcnt(6)
	v_mfma_f32_32x32x16_bf16 v[238:253], v[182:185], v[190:193], v[238:253]
	ds_read_b128 v[182:185], v254 offset:96
	ds_read_b128 v[190:193], v211 offset:96
	s_waitcnt lgkmcnt(2)
	v_mfma_f32_32x32x16_bf16 v[238:253], v[178:181], v[186:189], v[238:253]
	ds_read_b128 v[178:181], v254 offset:128
	ds_read_b128 v[186:189], v211 offset:128
	s_waitcnt lgkmcnt(2)
	v_mfma_f32_32x32x16_bf16 v[238:253], v[182:185], v[190:193], v[238:253]
	ds_read_b128 v[182:185], v254 offset:160
	ds_read_b128 v[190:193], v211 offset:160
	v_mfma_f32_32x32x16_bf16 v[112:127], v[228:231], v[156:159], v[112:127]
	v_mfma_f32_32x32x16_bf16 v[96:111], v[228:231], v[132:135], v[96:111]
	ds_read_b128 v[228:231], v136 offset:9216
	s_nop 7
	v_mfma_f32_32x32x16_bf16 v[80:95], v[232:235], v[156:159], v[80:95]
	v_exp_f32_e32 v238, v238
	v_exp_f32_e32 v239, v239
	v_exp_f32_e32 v240, v240
	v_exp_f32_e32 v241, v241
	v_exp_f32_e32 v242, v242
	v_exp_f32_e32 v243, v243
	v_exp_f32_e32 v244, v244
	v_mfma_f32_32x32x16_bf16 v[64:79], v[232:235], v[132:135], v[64:79]
	ds_read_b128 v[232:235], v136 offset:13824
	v_exp_f32_e32 v245, v245
	v_exp_f32_e32 v246, v246
	v_exp_f32_e32 v247, v247
	v_exp_f32_e32 v248, v248
	v_exp_f32_e32 v249, v249
	v_exp_f32_e32 v250, v250
	v_exp_f32_e32 v251, v251
	s_waitcnt lgkmcnt(1)
; #define LAS __attribute__((address_space(3)))
; #define SB0() __builtin_amdgcn_sched_barrier(0)
; template <bool SHIFT> DI void attn_unit(LAS unsigned char* lds, const bf16_t* Qb, const bf16_t* Kb, const bf16_t* Vt, bf16_t* concat,
;                   int b, int h, int qt, float shift2, float lam, int lam_init_bits, const float* subln_g) {
;     ...
;     const bool lag = wid >= 4;
;     bf16x8 Pc[2][2];
; #pragma unroll
;     for (int m = 0; m < 2; ++m)
; #pragma unroll
;         for (int g = 0; g < 2; ++g) { u32x4 z = {0u, 0u, 0u, 0u}; Pc[m][g] = __builtin_bit_cast(bf16x8, z); }
;     const LAS unsigned char* vold = lds + V_OFF + r * VP + hh * 16;
;     int vcur = 0;
;     for (int kt = 0; kt < nkt; ++kt) {
;         const int cur = kt & 1, nx = cur ^ 1;
;         const int vnx = vcur == 2 ? 0 : vcur + 1;
;         const bool pf = (kt + 1 < nkt);
;         const size_t ko = (size_t)(kt + 1) * 64;
;         if (pf) { *(LAS u32x4*)(lds + K_OFF + nx * K_BYTES + krow0 * QP + kc * 16) = sg0; *(LAS u32x4*)(lds + K_OFF + nx * K_BYTES + (krow0 + 32) * QP + kc * 16) = sg1;
;             sg0 = *(const u32x4*)(vg + (size_t)(vrow0) * TPB + ko + vc * 8); sg1 = *(const u32x4*)(vg + (size_t)(vrow0 + 64) * TPB + ko + vc * 8); }
;         const LAS unsigned char* kb = lds + K_OFF + cur * K_BYTES + r * QP + hh * 16;
;         const LAS unsigned char* vb = lds + V_OFF + vcur * V_BYTES + r * VP + hh * 16;
; #pragma unroll
;         for (int half = 0; half < 2; ++half) {
;             if (lag) PVH(Pc, vold);
;             QKEXP(Pc, half);
;             if (half == 0 && pf) { *(LAS u32x4*)(lds + V_OFF + vnx * V_BYTES + vrow0 * VP + vc * 16) = sg0; *(LAS u32x4*)(lds + V_OFF + vnx * V_BYTES + (vrow0 + 64) * VP + vc * 16) = sg1;
;                 if (kt + 2 < nkt) { sg0 = *(const u32x4*)(kg + (ko + 64 + krow0) * 1024 + kc * 8); sg1 = *(const u32x4*)(kg + (ko + 64 + krow0 + 32) * 1024 + kc * 8); } }
;             vold = vb + half * 64;
;             SB0();
;             if (!lag) PVH(Pc, vold);
	v_mfma_f32_32x32x16_bf16 v[32:47], v[228:231], v[156:159], v[32:47]
	v_exp_f32_e32 v252, v252
	v_exp_f32_e32 v253, v253
	v_add_f32_e32 v174, v238, v239
	v_add_f32_e32 v175, v240, v241
	v_add_f32_e32 v174, v174, v242
	v_add_f32_e32 v175, v175, v243
	v_add_f32_e32 v174, v174, v244
	v_mfma_f32_32x32x16_bf16 v[48:63], v[228:231], v[132:135], v[48:63]
	ds_read_b128 v[228:231], v136 offset:32
	v_add_f32_e32 v175, v175, v245
	v_add_f32_e32 v174, v174, v246
	v_add_f32_e32 v175, v175, v247
	v_add_f32_e32 v174, v174, v248
	v_add_f32_e32 v175, v175, v249
	v_add_f32_e32 v174, v174, v250
	v_add_f32_e32 v175, v175, v251
	s_waitcnt lgkmcnt(1)
	v_mfma_f32_32x32x16_bf16 v[16:31], v[232:235], v[156:159], v[16:31]
	v_add_f32_e32 v174, v174, v252
	v_add_f32_e32 v175, v175, v253
	v_add_f32_e32 v174, v174, v175
	v_add_f32_e32 v165, v165, v174
	v_cvt_pk_bf16_f32 v194, v238, v239
	v_cvt_pk_bf16_f32 v195, v240, v241
	v_mfma_f32_32x32x16_bf16 v[0:15], v[232:235], v[132:135], v[0:15]
	ds_read_b128 v[232:235], v136 offset:4640
	v_cvt_pk_bf16_f32 v196, v242, v243
	v_cvt_pk_bf16_f32 v197, v244, v245
	v_cvt_pk_bf16_f32 v198, v246, v247
	v_cvt_pk_bf16_f32 v199, v248, v249
	v_cvt_pk_bf16_f32 v200, v250, v251
	v_cvt_pk_bf16_f32 v201, v252, v253
	v_mfma_f32_32x32x16_bf16 v[238:253], v[178:181], v[186:189], 0
	ds_read_b128 v[178:181], v254 offset:192
	ds_read_b128 v[186:189], v211 offset:192
	v_mfma_f32_32x32x16_bf16 v[238:253], v[182:185], v[190:193], v[238:253]
	ds_read_b128 v[182:185], v254 offset:224
	ds_read_b128 v[190:193], v211 offset:224
	s_waitcnt lgkmcnt(2)
	v_mfma_f32_32x32x16_bf16 v[238:253], v[178:181], v[186:189], v[238:253]
	ds_read_b128 v[178:181], v254 offset:8704
	ds_read_b128 v[186:189], v211
	s_waitcnt lgkmcnt(2)
	v_mfma_f32_32x32x16_bf16 v[238:253], v[182:185], v[190:193], v[238:253]
	ds_read_b128 v[182:185], v254 offset:8736
	ds_read_b128 v[190:193], v211 offset:32
	v_mfma_f32_32x32x16_bf16 v[112:127], v[228:231], v[152:155], v[112:127]
	v_mfma_f32_32x32x16_bf16 v[96:111], v[228:231], v[128:131], v[96:111]
	ds_read_b128 v[228:231], v136 offset:9248
	s_nop 7
	v_mfma_f32_32x32x16_bf16 v[80:95], v[232:235], v[152:155], v[80:95]
	v_exp_f32_e32 v238, v238
	v_exp_f32_e32 v239, v239
	v_exp_f32_e32 v240, v240
	v_exp_f32_e32 v241, v241
	v_exp_f32_e32 v242, v242
	v_exp_f32_e32 v243, v243
	v_exp_f32_e32 v244, v244
	v_mfma_f32_32x32x16_bf16 v[64:79], v[232:235], v[128:131], v[64:79]
	ds_read_b128 v[232:235], v136 offset:13856
	v_exp_f32_e32 v245, v245
	v_exp_f32_e32 v246, v246
	v_exp_f32_e32 v247, v247
	v_exp_f32_e32 v248, v248
	v_exp_f32_e32 v249, v249
	v_exp_f32_e32 v250, v250
	v_exp_f32_e32 v251, v251
	s_waitcnt lgkmcnt(1)
	v_mfma_f32_32x32x16_bf16 v[32:47], v[228:231], v[152:155], v[32:47]
	v_exp_f32_e32 v252, v252
	v_exp_f32_e32 v253, v253
	v_add_f32_e32 v174, v238, v239
	v_add_f32_e32 v175, v240, v241
	v_add_f32_e32 v174, v174, v242
	v_add_f32_e32 v175, v175, v243
	v_add_f32_e32 v174, v174, v244
	v_mfma_f32_32x32x16_bf16 v[48:63], v[228:231], v[128:131], v[48:63]
	ds_read_b128 v[228:231], v217
	v_add_f32_e32 v175, v175, v245
	v_add_f32_e32 v174, v174, v246
	v_add_f32_e32 v175, v175, v247
	v_add_f32_e32 v174, v174, v248
	v_add_f32_e32 v175, v175, v249
	v_add_f32_e32 v174, v174, v250
	v_add_f32_e32 v175, v175, v251
	s_waitcnt lgkmcnt(1)
	v_mfma_f32_32x32x16_bf16 v[16:31], v[232:235], v[152:155], v[16:31]
	v_add_f32_e32 v174, v174, v252
	v_add_f32_e32 v175, v175, v253
	v_add_f32_e32 v174, v174, v175
	v_add_f32_e32 v164, v164, v174
	v_cvt_pk_bf16_f32 v202, v238, v239
	v_cvt_pk_bf16_f32 v203, v240, v241
	v_mfma_f32_32x32x16_bf16 v[0:15], v[232:235], v[128:131], v[0:15]
	ds_read_b128 v[232:235], v217 offset:4608
	v_cvt_pk_bf16_f32 v204, v242, v243
	v_cvt_pk_bf16_f32 v205, v244, v245
	v_cvt_pk_bf16_f32 v206, v246, v247
	v_cvt_pk_bf16_f32 v207, v248, v249
	v_cvt_pk_bf16_f32 v208, v250, v251
	v_cvt_pk_bf16_f32 v209, v252, v253
	s_waitcnt vmcnt(0)
	ds_write_b128 v218, v[144:147]
	ds_write_b128 v219, v[148:151]
	s_cmp_ge_u32 s34, s35
	s_cbranch_scc1 .Lattn_kskip_s
	v_lshl_add_u64 v[170:171], v[166:167], 0, s[22:23]
	v_add_co_u32_e32 v172, vcc, 0xc5c8000, v170
	s_nop 1
	v_addc_co_u32_e32 v173, vcc, 0, v171, vcc
	v_add_co_u32_e32 v170, vcc, 0xc5d8000, v170
	s_nop 1
	v_addc_co_u32_e32 v171, vcc, 0, v171, vcc
	global_load_dwordx4 v[144:147], v[172:173], off
	global_load_dwordx4 v[148:151], v[170:171], off
; #define LAS __attribute__((address_space(3)))
; #define SB0() __builtin_amdgcn_sched_barrier(0)
; template <bool SHIFT> DI void attn_unit(LAS unsigned char* lds, const bf16_t* Qb, const bf16_t* Kb, const bf16_t* Vt, bf16_t* concat,
;                   int b, int h, int qt, float shift2, float lam, int lam_init_bits, const float* subln_g) {
;     ...
;     const bool lag = wid >= 4;
;     bf16x8 Pc[2][2];
; #pragma unroll
;     for (int m = 0; m < 2; ++m)
; #pragma unroll
;         for (int g = 0; g < 2; ++g) { u32x4 z = {0u, 0u, 0u, 0u}; Pc[m][g] = __builtin_bit_cast(bf16x8, z); }
;     const LAS unsigned char* vold = lds + V_OFF + r * VP + hh * 16;
;     int vcur = 0;
;     for (int kt = 0; kt < nkt; ++kt) {
;         const int cur = kt & 1, nx = cur ^ 1;
;         const int vnx = vcur == 2 ? 0 : vcur + 1;
;         const bool pf = (kt + 1 < nkt);
;         const size_t ko = (size_t)(kt + 1) * 64;
;         if (pf) { *(LAS u32x4*)(lds + K_OFF + nx * K_BYTES + krow0 * QP + kc * 16) = sg0; *(LAS u32x4*)(lds + K_OFF + nx * K_BYTES + (krow0 + 32) * QP + kc * 16) = sg1;
;             sg0 = *(const u32x4*)(vg + (size_t)(vrow0) * TPB + ko + vc * 8); sg1 = *(const u32x4*)(vg + (size_t)(vrow0 + 64) * TPB + ko + vc * 8); }
;         const LAS unsigned char* kb = lds + K_OFF + cur * K_BYTES + r * QP + hh * 16;
;         const LAS unsigned char* vb = lds + V_OFF + vcur * V_BYTES + r * VP + hh * 16;
; #pragma unroll
;         for (int half = 0; half < 2; ++half) {
;             if (lag) PVH(Pc, vold);
;             QKEXP(Pc, half);
;             if (half == 0 && pf) { *(LAS u32x4*)(lds + V_OFF + vnx * V_BYTES + vrow0 * VP + vc * 16) = sg0; *(LAS u32x4*)(lds + V_OFF + vnx * V_BYTES + (vrow0 + 64) * VP + vc * 16) = sg1;
;                 if (kt + 2 < nkt) { sg0 = *(const u32x4*)(kg + (ko + 64 + krow0) * 1024 + kc * 8); sg1 = *(const u32x4*)(kg + (ko + 64 + krow0 + 32) * 1024 + kc * 8); } }
;             vold = vb + half * 64;
;             SB0();
;             if (!lag) PVH(Pc, vold);
;         }
;         __syncthreads();
;         vcur = vnx;
.Lattn_kskip_s:
	v_mfma_f32_32x32x16_bf16 v[238:253], v[178:181], v[186:189], 0
	ds_read_b128 v[178:181], v254 offset:8768
	ds_read_b128 v[186:189], v211 offset:64
	v_mfma_f32_32x32x16_bf16 v[238:253], v[182:185], v[190:193], v[238:253]
	ds_read_b128 v[182:185], v254 offset:8800
	ds_read_b128 v[190:193], v211 offset:96
	s_waitcnt lgkmcnt(2)
	v_mfma_f32_32x32x16_bf16 v[238:253], v[178:181], v[186:189], v[238:253]
	ds_read_b128 v[178:181], v254 offset:8832
	ds_read_b128 v[186:189], v211 offset:128
	s_waitcnt lgkmcnt(2)
	v_mfma_f32_32x32x16_bf16 v[238:253], v[182:185], v[190:193], v[238:253]
	ds_read_b128 v[182:185], v254 offset:8864
	ds_read_b128 v[190:193], v211 offset:160
	v_mfma_f32_32x32x16_bf16 v[112:127], v[228:231], v[194:197], v[112:127]
	v_mfma_f32_32x32x16_bf16 v[96:111], v[228:231], v[202:205], v[96:111]
	ds_read_b128 v[228:231], v217 offset:9216
	s_nop 7
	v_mfma_f32_32x32x16_bf16 v[80:95], v[232:235], v[194:197], v[80:95]
	v_exp_f32_e32 v238, v238
	v_exp_f32_e32 v239, v239
	v_exp_f32_e32 v240, v240
	v_exp_f32_e32 v241, v241
	v_exp_f32_e32 v242, v242
	v_exp_f32_e32 v243, v243
	v_exp_f32_e32 v244, v244
	v_mfma_f32_32x32x16_bf16 v[64:79], v[232:235], v[202:205], v[64:79]
	ds_read_b128 v[232:235], v217 offset:13824
	v_exp_f32_e32 v245, v245
	v_exp_f32_e32 v246, v246
	v_exp_f32_e32 v247, v247
	v_exp_f32_e32 v248, v248
	v_exp_f32_e32 v249, v249
	v_exp_f32_e32 v250, v250
	v_exp_f32_e32 v251, v251
	s_waitcnt lgkmcnt(1)
	v_mfma_f32_32x32x16_bf16 v[32:47], v[228:231], v[194:197], v[32:47]
	v_exp_f32_e32 v252, v252
	v_exp_f32_e32 v253, v253
	v_add_f32_e32 v174, v238, v239
	v_add_f32_e32 v175, v240, v241
	v_add_f32_e32 v174, v174, v242
	v_add_f32_e32 v175, v175, v243
	v_add_f32_e32 v174, v174, v244
	v_mfma_f32_32x32x16_bf16 v[48:63], v[228:231], v[202:205], v[48:63]
	ds_read_b128 v[228:231], v217 offset:32
	v_add_f32_e32 v175, v175, v245
	v_add_f32_e32 v174, v174, v246
	v_add_f32_e32 v175, v175, v247
	v_add_f32_e32 v174, v174, v248
	v_add_f32_e32 v175, v175, v249
	v_add_f32_e32 v174, v174, v250
	v_add_f32_e32 v175, v175, v251
	s_waitcnt lgkmcnt(1)
	v_mfma_f32_32x32x16_bf16 v[16:31], v[232:235], v[194:197], v[16:31]
	v_add_f32_e32 v174, v174, v252
	v_add_f32_e32 v175, v175, v253
	v_add_f32_e32 v174, v174, v175
	v_add_f32_e32 v165, v165, v174
	v_cvt_pk_bf16_f32 v156, v238, v239
	v_cvt_pk_bf16_f32 v157, v240, v241
	v_mfma_f32_32x32x16_bf16 v[0:15], v[232:235], v[202:205], v[0:15]
	ds_read_b128 v[232:235], v217 offset:4640
	v_cvt_pk_bf16_f32 v158, v242, v243
	v_cvt_pk_bf16_f32 v159, v244, v245
	v_cvt_pk_bf16_f32 v152, v246, v247
	v_cvt_pk_bf16_f32 v153, v248, v249
	v_cvt_pk_bf16_f32 v154, v250, v251
	v_cvt_pk_bf16_f32 v155, v252, v253
	v_mfma_f32_32x32x16_bf16 v[238:253], v[178:181], v[186:189], 0
	ds_read_b128 v[178:181], v254 offset:8896
	ds_read_b128 v[186:189], v211 offset:192
	v_mfma_f32_32x32x16_bf16 v[238:253], v[182:185], v[190:193], v[238:253]
	ds_read_b128 v[182:185], v254 offset:8928
	ds_read_b128 v[190:193], v211 offset:224
	s_waitcnt lgkmcnt(2)
	v_mfma_f32_32x32x16_bf16 v[238:253], v[178:181], v[186:189], v[238:253]
	s_waitcnt lgkmcnt(0)
	v_mfma_f32_32x32x16_bf16 v[238:253], v[182:185], v[190:193], v[238:253]
	v_mfma_f32_32x32x16_bf16 v[112:127], v[228:231], v[198:201], v[112:127]
	v_mfma_f32_32x32x16_bf16 v[96:111], v[228:231], v[206:209], v[96:111]
	ds_read_b128 v[228:231], v217 offset:9248
	s_nop 7
	v_mfma_f32_32x32x16_bf16 v[80:95], v[232:235], v[198:201], v[80:95]
	v_exp_f32_e32 v238, v238
	v_exp_f32_e32 v239, v239
	v_exp_f32_e32 v240, v240
	v_exp_f32_e32 v241, v241
	v_exp_f32_e32 v242, v242
	v_exp_f32_e32 v243, v243
	v_exp_f32_e32 v244, v244
	v_mfma_f32_32x32x16_bf16 v[64:79], v[232:235], v[206:209], v[64:79]
	ds_read_b128 v[232:235], v217 offset:13856
	v_exp_f32_e32 v245, v245
	v_exp_f32_e32 v246, v246
	v_exp_f32_e32 v247, v247
	v_exp_f32_e32 v248, v248
	v_exp_f32_e32 v249, v249
	v_exp_f32_e32 v250, v250
	v_exp_f32_e32 v251, v251
	s_waitcnt lgkmcnt(1)
	v_mfma_f32_32x32x16_bf16 v[32:47], v[228:231], v[198:201], v[32:47]
	v_exp_f32_e32 v252, v252
	v_exp_f32_e32 v253, v253
	v_add_f32_e32 v174, v238, v239
	v_add_f32_e32 v175, v240, v241
	v_add_f32_e32 v174, v174, v242
	v_add_f32_e32 v175, v175, v243
	v_add_f32_e32 v174, v174, v244
	v_mfma_f32_32x32x16_bf16 v[48:63], v[228:231], v[206:209], v[48:63]
	v_add_f32_e32 v175, v175, v245
	v_add_f32_e32 v174, v174, v246
	v_add_f32_e32 v175, v175, v247
	v_add_f32_e32 v174, v174, v248
	v_add_f32_e32 v175, v175, v249
	v_add_f32_e32 v174, v174, v250
	v_add_f32_e32 v175, v175, v251
	s_waitcnt lgkmcnt(0)
	v_mfma_f32_32x32x16_bf16 v[16:31], v[232:235], v[198:201], v[16:31]
	v_add_f32_e32 v174, v174, v252
	v_add_f32_e32 v175, v175, v253
	v_add_f32_e32 v174, v174, v175
	v_add_f32_e32 v164, v164, v174
	v_cvt_pk_bf16_f32 v132, v238, v239
	v_cvt_pk_bf16_f32 v133, v240, v241
	v_mfma_f32_32x32x16_bf16 v[0:15], v[232:235], v[206:209], v[0:15]
	v_cvt_pk_bf16_f32 v134, v242, v243
	v_cvt_pk_bf16_f32 v135, v244, v245
	v_cvt_pk_bf16_f32 v128, v246, v247
	v_cvt_pk_bf16_f32 v129, v248, v249
	v_cvt_pk_bf16_f32 v130, v250, v251
	v_cvt_pk_bf16_f32 v131, v252, v253
	s_waitcnt lgkmcnt(0)
	s_add_u32 s22, s22, 0x20000
	s_addc_u32 s23, s23, 0
	s_add_i32 s34, s34, 1
	v_add_u32_e32 v136, 64, v217
	s_cmp_eq_u32 s36, s22
	v_lshl_add_u64 v[168:169], v[168:169], 0, s[56:57]
	s_barrier
	s_cbranch_scc1 .LBB0_545
	s_mov_b32 s40, s65
	s_branch .LBB0_533
